# v30 + MLA tile loop edge edits: end-of-step scalar moves before the barrier, m0 written directly in the LDS-DMA heads
# speedup vs baseline: 1.0007x; 1.0007x over previous
; template <int DQK>
; __device__ __forceinline__ void attn_pass4(LAS unsigned char* lds, const bf16* Qp, int qpitch, const bf16* Kp, int kpitch, const bf16* Vp, int vpitch, int q0, f32x16 (&o)[4], float (&rl)[16]) {
;     ...
;         for (int t = 0; t < NT; ++t) {
;             const int vnext = ATT_VNEXT(vcur);
;             if (t + 1 < NT) ATT_DMA(t + 1, (t + 1) & 1, vnext);
.LBB0_2151:
	s_add_i32 s61, s78, 1
	s_cmp_lg_u32 s78, 2
	s_cselect_b32 s76, s61, 0
	s_add_i32 s77, s60, 1
	s_cmp_ge_u32 s77, s69
	s_cbranch_scc1 .LBB0_2155_p0
	s_bitcmp1_b32 s77, 0
	s_cselect_b32 s61, 0x6400, 0
	s_add_i32 m0, s61, s2
	s_nop 0
	global_load_lds_dwordx4 v180, s[56:57]
	s_add_i32 m0, s61, s72
	s_nop 0
	global_load_lds_dwordx4 v182, s[56:57]
	s_add_i32 m0, s61, s73
	s_nop 0
	global_load_lds_dwordx4 v184, s[56:57]
	s_andn2_b64 vcc, exec, s[12:13]
	s_cbranch_vccnz .LBB0_2154_p0
	s_add_i32 m0, s61, s74
	s_nop 0
	global_load_lds_dwordx4 v190, s[56:57]
.LBB0_2154_p0:
	s_mul_i32 s61, s76, 0x5000
	s_add_i32 s61, s24, s61

	s_mov_b32 m0, s61
	s_nop 0
	global_load_lds_dwordx4 v186, s[58:59]

	s_add_i32 m0, s61, 0x2000
	s_nop 0
	global_load_lds_dwordx4 v188, s[58:59]
	v_readfirstlane_b32 s32, v242
	s_cmpk_gt_u32 s32, 0xff
	s_cbranch_scc1 .Lskip_v2_2_p0

	s_addk_i32 s61, 0x4000
	s_mov_b32 m0, s61
	s_nop 0
	global_load_lds_dwordx4 v192, s[58:59]

; #define ATT_BAR() asm volatile("s_waitcnt lgkmcnt(0)\n\ts_barrier" ::: "memory")
; #define ATT_BAR() asm volatile("s_waitcnt vmcnt(0) lgkmcnt(0)\n\ts_barrier" ::: "memory")
; template <int DQK>
; __device__ __forceinline__ void attn_pass4(LAS unsigned char* lds, const bf16* Qp, int qpitch, const bf16* Kp, int kpitch, const bf16* Vp, int vpitch, int q0, f32x16 (&o)[4], float (&rl)[16]) {
;     ...
;         for (int t = 0; t < NT; ++t) {
;             const int vnext = ATT_VNEXT(vcur);
;             if (t + 1 < NT) ATT_DMA(t + 1, (t + 1) & 1, vnext);
;             if (ATT_VIS(t)) { ATT_A(t); ATT_B(vcur); }
;             vcur = vnext;
;             ATT_BAR();
.Lnovis_p0:
.Lend_p0:
	s_add_i32 s75, s75, 64
	s_add_u32 s58, s58, 0x20000
	s_addc_u32 s59, s59, 0
	s_add_u32 s56, s56, 0x30000
	s_addc_u32 s57, s57, 0
	s_mov_b32 s93, s78
	s_mov_b32 s78, s76
	s_mov_b32 s60, s77
	s_waitcnt vmcnt(0) lgkmcnt(0)
	s_barrier


; #define ATT_BAR() asm volatile("s_waitcnt lgkmcnt(0)\n\ts_barrier" ::: "memory")
; #define ATT_BAR() asm volatile("s_waitcnt vmcnt(0) lgkmcnt(0)\n\ts_barrier" ::: "memory")
; template <int DQK>
; __device__ __forceinline__ void attn_pass4(LAS unsigned char* lds, const bf16* Qp, int qpitch, const bf16* Kp, int kpitch, const bf16* Vp, int vpitch, int q0, f32x16 (&o)[4], float (&rl)[16]) {
;     ...
;         for (int t = 0; t < NT; ++t) {
;             const int vnext = ATT_VNEXT(vcur);
;             if (t + 1 < NT) ATT_DMA(t + 1, (t + 1) & 1, vnext);
;             if (ATT_VIS(t)) { ATT_A(t); ATT_B(vcur); }
;             vcur = vnext;
;             ATT_BAR();
.Lend_ba:
	s_add_i32 s75, s75, 64
	s_add_u32 s58, s58, 0x20000
	s_addc_u32 s59, s59, 0
	s_add_u32 s56, s56, 0x30000
	s_addc_u32 s57, s57, 0
	s_mov_b32 s93, s78
	s_mov_b32 s78, s76
	s_mov_b32 s60, s77
	s_waitcnt vmcnt(0) lgkmcnt(0)
	s_barrier

	s_add_i32 s61, s78, 1
	s_cmp_lg_u32 s78, 2
	s_cselect_b32 s76, s61, 0
	s_add_i32 s77, s60, 1
	s_cmp_ge_u32 s77, s69
	s_cbranch_scc1 .LBB0_2155_ab
	s_bitcmp1_b32 s77, 0
	s_cselect_b32 s61, 0x6400, 0
	s_add_i32 m0, s61, s2
	s_nop 0
	global_load_lds_dwordx4 v180, s[56:57]
	s_add_i32 m0, s61, s72
	s_nop 0
	global_load_lds_dwordx4 v182, s[56:57]
	s_add_i32 m0, s61, s73
	s_nop 0
	global_load_lds_dwordx4 v184, s[56:57]
	s_andn2_b64 vcc, exec, s[12:13]
	s_cbranch_vccnz .LBB0_2154_ab
	s_add_i32 m0, s61, s74
	s_nop 0
	global_load_lds_dwordx4 v190, s[56:57]

; #define ATT_BAR() asm volatile("s_waitcnt lgkmcnt(0)\n\ts_barrier" ::: "memory")
; #define ATT_BAR() asm volatile("s_waitcnt vmcnt(0) lgkmcnt(0)\n\ts_barrier" ::: "memory")
; template <int DQK>
; __device__ __forceinline__ void attn_pass4(LAS unsigned char* lds, const bf16* Qp, int qpitch, const bf16* Kp, int kpitch, const bf16* Vp, int vpitch, int q0, f32x16 (&o)[4], float (&rl)[16]) {
;     ...
;         for (int t = 0; t < NT; ++t) {
;             const int vnext = ATT_VNEXT(vcur);
;             if (t + 1 < NT) ATT_DMA(t + 1, (t + 1) & 1, vnext);
;             if (ATT_VIS(t)) { ATT_A(t); ATT_B(vcur); }
;             vcur = vnext;
;             ATT_BAR();
.Lend_ab:
	s_add_i32 s75, s75, 64
	s_add_u32 s58, s58, 0x20000
	s_addc_u32 s59, s59, 0
	s_add_u32 s56, s56, 0x30000
	s_addc_u32 s57, s57, 0
	s_mov_b32 s93, s78
	s_mov_b32 s78, s76
	s_mov_b32 s60, s77
	s_waitcnt vmcnt(0) lgkmcnt(0)
	s_barrier

; template <int DQK>
; __device__ __forceinline__ void attn_pass4(LAS unsigned char* lds, const bf16* Qp, int qpitch, const bf16* Kp, int kpitch, const bf16* Vp, int vpitch, int q0, f32x16 (&o)[4], float (&rl)[16]) {
;     ...
;         for (int t = 0; t < NT; ++t) {
;             const int vnext = ATT_VNEXT(vcur);
;             if (t + 1 < NT) ATT_DMA(t + 1, (t + 1) & 1, vnext);
	s_add_i32 s61, s77, 1
	s_cmp_eq_u32 s61, s69
	s_cbranch_scc0 .Lpipe_loop
	s_add_i32 s61, s78, 1
	s_cmp_lg_u32 s78, 2
	s_cselect_b32 s76, s61, 0
	s_add_i32 s77, s60, 1
	s_cmp_ge_u32 s77, s69
	s_cbranch_scc1 .LBB0_2155_fin
	s_bitcmp1_b32 s77, 0
	s_cselect_b32 s61, 0x6400, 0
	s_add_i32 m0, s61, s2
	s_nop 0
	global_load_lds_dwordx4 v180, s[56:57]
	s_add_i32 m0, s61, s72
	s_nop 0
	global_load_lds_dwordx4 v182, s[56:57]
	s_add_i32 m0, s61, s73
	s_nop 0
	global_load_lds_dwordx4 v184, s[56:57]
	s_andn2_b64 vcc, exec, s[12:13]
	s_cbranch_vccnz .LBB0_2154_fin
	s_add_i32 m0, s61, s74
	s_nop 0
	global_load_lds_dwordx4 v190, s[56:57]

; #define ATT_BAR() asm volatile("s_waitcnt lgkmcnt(0)\n\ts_barrier" ::: "memory")
; #define ATT_BAR() asm volatile("s_waitcnt vmcnt(0) lgkmcnt(0)\n\ts_barrier" ::: "memory")
; template <int DQK>
; __device__ __forceinline__ void attn_pass4(LAS unsigned char* lds, const bf16* Qp, int qpitch, const bf16* Kp, int kpitch, const bf16* Vp, int vpitch, int q0, f32x16 (&o)[4], float (&rl)[16]) {
;     ...
;         for (int t = 0; t < NT; ++t) {
;             const int vnext = ATT_VNEXT(vcur);
;             if (t + 1 < NT) ATT_DMA(t + 1, (t + 1) & 1, vnext);
;             if (t > 0 && ATT_VIS(t - 1)) ATT_B(vprev);
;             if (ATT_VIS(t)) ATT_A(t);
;             vprev = vcur; vcur = vnext;
;             ATT_BAR();
.Lend_fin:
	s_add_i32 s75, s75, 64
	s_add_u32 s58, s58, 0x20000
	s_addc_u32 s59, s59, 0
	s_add_u32 s56, s56, 0x30000
	s_addc_u32 s57, s57, 0
	s_mov_b32 s93, s78
	s_mov_b32 s78, s76
	s_mov_b32 s60, s77
	s_waitcnt vmcnt(0) lgkmcnt(0)
	s_barrier

; template <int DQK>
; __device__ __forceinline__ void attn_pass4(LAS unsigned char* lds, const bf16* Qp, int qpitch, const bf16* Kp, int kpitch, const bf16* Vp, int vpitch, int q0, f32x16 (&o)[4], float (&rl)[16]) {
;     ...
;         if (ATT_VIS(NT - 1)) ATT_B(vprev);
	s_sub_i32 s61, s75, 0x7f
	s_cmp_gt_i32 s61, s25
	s_cbranch_scc1 .Lpipe_done
	s_mul_i32 s94, s93, 0x5000
	v_add_u32_e32 v4, s94, v203
	v_add_u32_e32 v5, 0xc800, v4
	s_setprio 1
	ds_read_b64_tr_b16 v[238:239], v4 offset:51200
	ds_read_b64_tr_b16 v[240:241], v4 offset:53760
	ds_read_b64_tr_b16 v[244:245], v4 offset:51264
	ds_read_b64_tr_b16 v[246:247], v4 offset:53824
	ds_read_b64_tr_b16 v[248:249], v4 offset:51328
	ds_read_b64_tr_b16 v[250:251], v4 offset:53888
	ds_read_b64_tr_b16 v[8:9], v4 offset:51392
	ds_read_b64_tr_b16 v[10:11], v4 offset:53952
	ds_read_b64_tr_b16 v[12:13], v4 offset:56320
	ds_read_b64_tr_b16 v[14:15], v4 offset:58880
	v_exp_f32_e32 v206, v206
	v_exp_f32_e32 v207, v207
	v_exp_f32_e32 v208, v208
	v_exp_f32_e32 v209, v209
	v_exp_f32_e32 v210, v210
	v_exp_f32_e32 v211, v211
	v_exp_f32_e32 v212, v212
	v_exp_f32_e32 v213, v213
	v_add_f32_e32 v252, v206, v207
	v_add_f32_e32 v253, v208, v209
	v_add_f32_e32 v254, v210, v211
	v_add_f32_e32 v205, v212, v213
	s_nop 0
	v_cvt_pk_bf16_f32 v206, v206, v207
	v_cvt_pk_bf16_f32 v207, v208, v209
	v_cvt_pk_bf16_f32 v208, v210, v211
	v_cvt_pk_bf16_f32 v209, v212, v213
	s_nop 1
	s_waitcnt lgkmcnt(8)
	v_mfma_f32_32x32x16_bf16 v[64:79], v[206:209], v[238:241], v[64:79]
	ds_read_b64_tr_b16 v[238:239], v4 offset:56384
	ds_read_b64_tr_b16 v[240:241], v4 offset:58944
	v_exp_f32_e32 v214, v214
	v_exp_f32_e32 v215, v215
	v_exp_f32_e32 v216, v216
	v_exp_f32_e32 v217, v217
	v_exp_f32_e32 v218, v218
	v_exp_f32_e32 v219, v219
	s_waitcnt lgkmcnt(8)
	v_mfma_f32_32x32x16_bf16 v[48:63], v[206:209], v[244:247], v[48:63]
	ds_read_b64_tr_b16 v[244:245], v4 offset:56448
	ds_read_b64_tr_b16 v[246:247], v4 offset:59008
	v_exp_f32_e32 v220, v220
	v_exp_f32_e32 v221, v221
	v_add_f32_e32 v252, v252, v214
	v_add_f32_e32 v253, v253, v215
	v_add_f32_e32 v254, v254, v216
	s_waitcnt lgkmcnt(8)
	v_mfma_f32_32x32x16_bf16 v[32:47], v[206:209], v[248:251], v[32:47]
	ds_read_b64_tr_b16 v[248:249], v4 offset:56512
	ds_read_b64_tr_b16 v[250:251], v4 offset:59072
	v_add_f32_e32 v205, v205, v217
	v_add_f32_e32 v252, v252, v218
	v_add_f32_e32 v253, v253, v219
	v_add_f32_e32 v254, v254, v220
	v_add_f32_e32 v205, v205, v221
	s_waitcnt lgkmcnt(8)
	v_mfma_f32_32x32x16_bf16 v[16:31], v[206:209], v[8:11], v[16:31]
	ds_read_b64_tr_b16 v[8:9], v4 offset:61440
	ds_read_b64_tr_b16 v[10:11], v4 offset:64000
	v_cvt_pk_bf16_f32 v214, v214, v215
	v_cvt_pk_bf16_f32 v215, v216, v217
	v_cvt_pk_bf16_f32 v216, v218, v219
	v_cvt_pk_bf16_f32 v217, v220, v221
	s_nop 1
	s_waitcnt lgkmcnt(8)
	v_mfma_f32_32x32x16_bf16 v[64:79], v[214:217], v[12:15], v[64:79]
	ds_read_b64_tr_b16 v[12:13], v4 offset:61504
	ds_read_b64_tr_b16 v[14:15], v4 offset:64064
	v_exp_f32_e32 v222, v222
	v_exp_f32_e32 v223, v223
	v_exp_f32_e32 v224, v224
	v_exp_f32_e32 v225, v225
	v_exp_f32_e32 v226, v226
	v_exp_f32_e32 v227, v227
	s_waitcnt lgkmcnt(8)
	v_mfma_f32_32x32x16_bf16 v[48:63], v[214:217], v[238:241], v[48:63]
	ds_read_b64_tr_b16 v[238:239], v4 offset:61568
	ds_read_b64_tr_b16 v[240:241], v4 offset:64128
	v_exp_f32_e32 v228, v228
	v_exp_f32_e32 v229, v229
	v_add_f32_e32 v252, v252, v222
	v_add_f32_e32 v253, v253, v223
	v_add_f32_e32 v254, v254, v224
	s_waitcnt lgkmcnt(8)
	v_mfma_f32_32x32x16_bf16 v[32:47], v[214:217], v[244:247], v[32:47]
	ds_read_b64_tr_b16 v[244:245], v4 offset:61632
	ds_read_b64_tr_b16 v[246:247], v4 offset:64192
	v_add_f32_e32 v205, v205, v225
	v_add_f32_e32 v252, v252, v226
	v_add_f32_e32 v253, v253, v227
	v_add_f32_e32 v254, v254, v228
	v_add_f32_e32 v205, v205, v229
	s_waitcnt lgkmcnt(8)
	v_mfma_f32_32x32x16_bf16 v[16:31], v[214:217], v[248:251], v[16:31]
	ds_read_b64_tr_b16 v[248:249], v5 offset:15360
	ds_read_b64_tr_b16 v[250:251], v5 offset:17920
	v_cvt_pk_bf16_f32 v222, v222, v223
	v_cvt_pk_bf16_f32 v223, v224, v225
	v_cvt_pk_bf16_f32 v224, v226, v227
	v_cvt_pk_bf16_f32 v225, v228, v229
	s_nop 1
	s_waitcnt lgkmcnt(8)
	v_mfma_f32_32x32x16_bf16 v[64:79], v[222:225], v[8:11], v[64:79]
	ds_read_b64_tr_b16 v[8:9], v5 offset:15424
	ds_read_b64_tr_b16 v[10:11], v5 offset:17984
	v_exp_f32_e32 v230, v230
	v_exp_f32_e32 v231, v231
	v_exp_f32_e32 v232, v232
	v_exp_f32_e32 v233, v233
	v_exp_f32_e32 v234, v234
	v_exp_f32_e32 v235, v235
	s_waitcnt lgkmcnt(8)
	v_mfma_f32_32x32x16_bf16 v[48:63], v[222:225], v[12:15], v[48:63]
	ds_read_b64_tr_b16 v[12:13], v5 offset:15488
	ds_read_b64_tr_b16 v[14:15], v5 offset:18048
	v_exp_f32_e32 v236, v236
	v_exp_f32_e32 v237, v237
	v_add_f32_e32 v252, v252, v230
	v_add_f32_e32 v253, v253, v231
	v_add_f32_e32 v254, v254, v232
	s_waitcnt lgkmcnt(8)
	v_mfma_f32_32x32x16_bf16 v[32:47], v[222:225], v[238:241], v[32:47]
	ds_read_b64_tr_b16 v[238:239], v5 offset:15552
	ds_read_b64_tr_b16 v[240:241], v5 offset:18112
	v_add_f32_e32 v205, v205, v233
	v_add_f32_e32 v252, v252, v234
	v_add_f32_e32 v253, v253, v235
	v_add_f32_e32 v254, v254, v236
	v_add_f32_e32 v205, v205, v237
	s_waitcnt lgkmcnt(8)
	v_mfma_f32_32x32x16_bf16 v[16:31], v[222:225], v[244:247], v[16:31]
	v_cvt_pk_bf16_f32 v230, v230, v231
	v_cvt_pk_bf16_f32 v231, v232, v233
	v_cvt_pk_bf16_f32 v232, v234, v235
	v_cvt_pk_bf16_f32 v233, v236, v237
	s_nop 1
	s_waitcnt lgkmcnt(6)
	v_mfma_f32_32x32x16_bf16 v[64:79], v[230:233], v[248:251], v[64:79]
	v_add_f32_e32 v252, v252, v253
	s_waitcnt lgkmcnt(4)
	v_mfma_f32_32x32x16_bf16 v[48:63], v[230:233], v[8:11], v[48:63]
	v_add_f32_e32 v254, v254, v205
	s_waitcnt lgkmcnt(2)
	v_mfma_f32_32x32x16_bf16 v[32:47], v[230:233], v[12:15], v[32:47]
	v_add_f32_e32 v252, v252, v254
	s_waitcnt lgkmcnt(0)
	v_mfma_f32_32x32x16_bf16 v[16:31], v[230:233], v[238:241], v[16:31]
	v_add_f32_e32 v2, v2, v252
	s_setprio 0
